# pre-pass B gains hoisted and k loads issued early, initial norm gain hoisted, tighter exact zero-skip bound (-151) for forgetting attention
# speedup vs baseline: 1.0304x; 1.0100x over previous
.LBB0_68:
	s_cmp_gt_i32 s14, 0x81ff
	v_mbcnt_lo_u32_b32 v24, -1, 0
	s_cbranch_scc1 .LBB0_77
	v_mbcnt_hi_u32_b32 v1, -1, v24
	v_and_b32_e32 v2, 64, v1
	v_add_u32_e32 v2, 64, v2
	v_xor_b32_e32 v4, 1, v1
	v_cmp_lt_i32_e32 vcc, v4, v2
	v_readlane_b32 s7, v251, 36
	s_ashr_i32 s2, s15, 31
	v_cndmask_b32_e32 v4, v1, v4, vcc
	v_lshlrev_b32_e32 v25, 2, v4
	v_xor_b32_e32 v4, 2, v1
	v_cmp_lt_i32_e32 vcc, v4, v2
	s_ashr_i32 s6, s7, 31
	s_add_u32 s8, s15, s7
	v_cndmask_b32_e32 v4, v1, v4, vcc
	v_lshlrev_b32_e32 v26, 2, v4
	v_xor_b32_e32 v4, 4, v1
	v_cmp_lt_i32_e32 vcc, v4, v2
	s_addc_u32 s9, s2, s6
	s_lshl_b64 s[6:7], s[8:9], 12
	v_cndmask_b32_e32 v4, v1, v4, vcc
	v_lshlrev_b32_e32 v27, 2, v4
	v_xor_b32_e32 v4, 8, v1
	v_cmp_lt_i32_e32 vcc, v4, v2
	s_add_u32 s6, s70, s6
	v_mov_b32_e32 v3, 0
	v_cndmask_b32_e32 v4, v1, v4, vcc
	v_lshlrev_b32_e32 v28, 2, v4
	v_xor_b32_e32 v4, 16, v1
	v_cmp_lt_i32_e32 vcc, v4, v2
	s_addc_u32 s7, s71, s7
	s_mov_b32 s10, s52
	v_cndmask_b32_e32 v4, v1, v4, vcc
	v_lshlrev_b32_e32 v29, 2, v4
	v_xor_b32_e32 v4, 32, v1
	v_cmp_lt_i32_e32 vcc, v4, v2
	v_lshlrev_b32_e32 v2, 4, v0
	s_ashr_i32 s11, s52, 31
	v_cndmask_b32_e32 v1, v1, v4, vcc
	v_lshl_add_u64 v[4:5], s[6:7], 0, v[2:3]
	s_mov_b64 s[6:7], 0x5f20800
	v_readlane_b32 s72, v251, 4
	v_lshl_add_u64 v[18:19], v[4:5], 0, s[6:7]
	s_lshl_b64 s[6:7], s[10:11], 12
	s_lshl_b64 s[8:9], s[8:9], 11
	v_readlane_b32 s76, v251, 8
	v_readlane_b32 s77, v251, 9
	s_add_u32 s8, s68, s8
	s_addc_u32 s9, s69, s9
	v_lshl_add_u64 v[16:17], s[76:77], 0, v[2:3]
	v_lshlrev_b32_e32 v2, 3, v0
	v_lshl_add_u64 v[2:3], s[8:9], 0, v[2:3]
	s_mov_b64 s[8:9], 0x400
	s_mov_b32 s3, 0
	v_lshlrev_b32_e32 v30, 2, v1
	v_lshl_add_u64 v[20:21], v[2:3], 0, s[8:9]
	s_lshl_b64 s[8:9], s[10:11], 11
	v_lshlrev_b32_e32 v31, 4, v0
	v_mov_b32_e32 v32, 0x358637bd
	v_readlane_b32 s73, v251, 5
	v_readlane_b32 s74, v251, 6
	v_readlane_b32 s75, v251, 7
	v_readlane_b32 s78, v251, 10
	v_readlane_b32 s79, v251, 11
	v_readlane_b32 s80, v251, 12
	v_readlane_b32 s81, v251, 13
	v_readlane_b32 s82, v251, 14
	v_readlane_b32 s83, v251, 15
	v_readlane_b32 s84, v251, 16
	v_readlane_b32 s85, v251, 17
	v_readlane_b32 s86, v251, 18
	v_readlane_b32 s87, v251, 19
	global_load_dwordx4 v[64:67], v[16:17], off
	global_load_dwordx4 v[68:71], v[16:17], off offset:1024
	global_load_dwordx4 v[72:75], v[16:17], off offset:2048
	global_load_dwordx4 v[76:79], v[16:17], off offset:3072
	s_waitcnt vmcnt(0)
	s_branch .LBB0_73

.LBB0_72:
	s_waitcnt vmcnt(3)
	global_store_dwordx4 v[18:19], v[12:15], off offset:-2048
	s_waitcnt vmcnt(3)
	global_store_dwordx4 v[18:19], v[8:11], off offset:-1024
	s_waitcnt vmcnt(3)
	global_store_dwordx4 v[18:19], v[4:7], off
	s_waitcnt vmcnt(3)
	global_store_dwordx4 v[18:19], v[0:3], off offset:1024
	v_pk_mul_f32 v[46:47], v[14:15], v[14:15]
	v_mov_b64_e32 v[34:35], v[64:65]
	v_mov_b64_e32 v[36:37], v[66:67]
	v_mov_b64_e32 v[38:39], v[68:69]
	v_mov_b64_e32 v[40:41], v[70:71]
	v_pk_mul_f32 v[50:51], v[12:13], v[12:13]
	v_mov_b64_e32 v[42:43], v[72:73]
	v_mov_b64_e32 v[44:45], v[74:75]
	v_pk_mov_b32 v[52:53], v[50:51], v[46:47] op_sel:[1,0]
	v_mov_b32_e32 v51, v47
	v_mov_b64_e32 v[46:47], v[76:77]
	v_mov_b64_e32 v[48:49], v[78:79]
	v_pk_add_f32 v[50:51], v[52:53], v[50:51]
	v_pk_mul_f32 v[52:53], v[10:11], v[10:11]
	v_pk_mul_f32 v[54:55], v[8:9], v[8:9]
	v_mul_f32_e32 v33, v0, v0
	v_pk_mov_b32 v[56:57], v[54:55], v[52:53] op_sel:[1,0]
	v_mov_b32_e32 v55, v53
	v_pk_add_f32 v[52:53], v[56:57], v[54:55]
	v_mul_f32_e32 v54, v1, v1
	v_pk_add_f32 v[50:51], v[50:51], v[50:51] op_sel:[0,1] op_sel_hi:[1,0]
	v_pk_add_f32 v[52:53], v[52:53], v[52:53] op_sel:[0,1] op_sel_hi:[1,0]
	v_mov_b32_e32 v51, v33
	v_mov_b32_e32 v53, v54
	v_pk_add_f32 v[50:51], v[50:51], v[52:53]
	v_mul_f32_e32 v52, v5, v5
	v_mul_f32_e32 v55, v2, v2
	v_pk_fma_f32 v[52:53], v[4:5], v[4:5], v[52:53] op_sel_hi:[1,1,0]
	v_mul_f32_e32 v54, v7, v7
	v_mul_f32_e32 v56, v3, v3
	v_mov_b32_e32 v53, v55
	v_pk_fma_f32 v[54:55], v[6:7], v[6:7], v[54:55] op_sel_hi:[1,1,0]
	s_add_i32 s14, s14, s52
	v_mov_b32_e32 v55, v56
	v_pk_add_f32 v[52:53], v[52:53], v[54:55]
	v_lshl_add_u64 v[18:19], v[18:19], 0, s[6:7]
	v_pk_add_f32 v[50:51], v[50:51], v[52:53]
	s_cmp_gt_i32 s14, 0x81ff
	v_add_f32_e32 v33, v50, v51
	ds_bpermute_b32 v50, v25, v33
	s_waitcnt lgkmcnt(0)
	v_add_f32_e32 v33, v33, v50
	ds_bpermute_b32 v50, v26, v33
	s_waitcnt lgkmcnt(0)
	v_add_f32_e32 v33, v33, v50
	ds_bpermute_b32 v50, v27, v33
	s_waitcnt lgkmcnt(0)
	v_add_f32_e32 v33, v33, v50
	ds_bpermute_b32 v50, v28, v33
	s_waitcnt lgkmcnt(0)
	v_add_f32_e32 v33, v33, v50
	ds_bpermute_b32 v50, v29, v33
	s_waitcnt lgkmcnt(0)
	v_add_f32_e32 v33, v33, v50
	ds_bpermute_b32 v50, v30, v33
	s_waitcnt lgkmcnt(0)
	v_add_f32_e32 v33, v33, v50
	v_fmamk_f32 v33, v33, 0x3a800000, v32
	v_rsq_f32_e32 v50, v33
	s_nop 0
	v_pk_mul_f32 v[12:13], v[12:13], v[50:51] op_sel_hi:[1,0]
	v_pk_mul_f32 v[14:15], v[14:15], v[50:51] op_sel_hi:[1,0]
	v_pk_mul_f32 v[8:9], v[8:9], v[50:51] op_sel_hi:[1,0]
	v_pk_mul_f32 v[10:11], v[10:11], v[50:51] op_sel_hi:[1,0]
	v_pk_mul_f32 v[4:5], v[4:5], v[50:51] op_sel_hi:[1,0]
	v_pk_mul_f32 v[6:7], v[6:7], v[50:51] op_sel_hi:[1,0]
	v_pk_mul_f32 v[0:1], v[0:1], v[50:51] op_sel_hi:[1,0]
	v_pk_mul_f32 v[2:3], v[2:3], v[50:51] op_sel_hi:[1,0]
	s_waitcnt vmcnt(3)
	v_pk_mul_f32 v[12:13], v[34:35], v[12:13]
	v_pk_mul_f32 v[14:15], v[36:37], v[14:15]
	s_waitcnt vmcnt(2)
	v_pk_mul_f32 v[8:9], v[38:39], v[8:9]
	v_pk_mul_f32 v[10:11], v[40:41], v[10:11]
	s_waitcnt vmcnt(1)
	v_pk_mul_f32 v[4:5], v[42:43], v[4:5]
	v_pk_mul_f32 v[6:7], v[44:45], v[6:7]
	s_waitcnt vmcnt(0)
	v_pk_mul_f32 v[0:1], v[0:1], v[46:47]
	v_pk_mul_f32 v[2:3], v[2:3], v[48:49]
	v_cvt_pk_bf16_f32 v12, v12, v13
	v_cvt_pk_bf16_f32 v13, v14, v15
	v_cvt_pk_bf16_f32 v8, v8, v9
	v_cvt_pk_bf16_f32 v9, v10, v11
	v_cvt_pk_bf16_f32 v4, v4, v5
	v_cvt_pk_bf16_f32 v5, v6, v7
	v_cvt_pk_bf16_f32 v0, v0, v1
	v_cvt_pk_bf16_f32 v1, v2, v3
	global_store_dwordx2 v[20:21], v[12:13], off offset:-1024
	global_store_dwordx2 v[20:21], v[8:9], off offset:-512
	global_store_dwordx2 v[20:21], v[4:5], off
	global_store_dwordx2 v[20:21], v[0:1], off offset:512
	v_lshl_add_u64 v[20:21], v[20:21], 0, s[8:9]
	s_cbranch_scc1 .LBB0_77

.LBB0_231:
	s_cmp_gt_i32 s12, -1
	s_cselect_b64 s[4:5], -1, 0
	s_lshl_b32 s0, s12, 8
	s_or_b32 s1, s0, 0x80
	s_cmp_lt_i32 s12, 0
	s_cselect_b64 s[18:19], -1, 0
	s_and_b64 s[2:3], s[18:19], exec
	s_cselect_b32 s21, 0, s1
	s_add_i32 s1, s21, 0x100
	v_readlane_b32 s2, v255, 24
	s_lshr_b32 s22, s1, 6
	v_readlane_b32 s3, v255, 25
	s_add_i32 s22, s22, -1
	s_andn2_b64 vcc, exec, s[2:3]
	s_mov_b64 s[12:13], -1
	s_cbranch_vccnz .LBB0_311
	s_waitcnt lgkmcnt(0)
	v_mov_b32_e32 v2, v156
	v_readlane_b32 s12, v255, 26
	v_readfirstlane_b32 s2, v2
	s_ashr_i32 s27, s2, 6
	s_lshl_b32 s23, s27, 5
	v_and_b32_e32 v126, 31, v2
	s_add_i32 s23, s23, s21
	v_readlane_b32 s13, v255, 27
	v_bfe_u32 v127, v2, 5, 1
	v_or_b32_e32 v16, s23, v126
	v_mov_b64_e32 v[0:1], s[12:13]
	s_movk_i32 s1, 0x1200
	v_mad_i64_i32 v[0:1], s[12:13], v16, s1, v[0:1]
	v_lshlrev_b32_e32 v112, 4, v127
	v_lshl_add_u64 v[0:1], v[0:1], 0, v[112:113]
	v_ashrrev_i32_e32 v17, 31, v16
	global_load_dwordx4 v[64:67], v[0:1], off offset:1344
	global_load_dwordx4 v[68:71], v[0:1], off offset:1376
	global_load_dwordx4 v[72:75], v[0:1], off offset:1408
	global_load_dwordx4 v[76:79], v[0:1], off offset:1440
	v_lshl_add_u64 v[0:1], v[16:17], 2, s[70:71]
	global_load_dword v130, v[0:1], off
	s_andn2_b64 vcc, exec, s[4:5]
	s_mov_b32 s16, 1
	s_cbranch_vccnz .LBB0_243
	v_cmp_gt_i32_e32 vcc, s22, v2
	v_mov_b32_e32 v0, 0
	s_and_saveexec_b64 s[4:5], vcc
	s_cbranch_execz .LBB0_235
	s_mov_b32 s1, s80
	s_lshl_b64 s[0:1], s[0:1], 2
	v_lshlrev_b32_e32 v0, 6, v2
	s_add_u32 s0, s70, s0
	v_ashrrev_i32_e32 v1, 31, v0
	s_addc_u32 s1, s71, s1
	v_lshl_add_u64 v[0:1], v[0:1], 2, s[70:71]
	global_load_dword v3, v113, s[0:1] offset:512
	s_nop 0
	global_load_dword v0, v[0:1], off offset:508
	s_mov_b32 s0, 0xc3170000
	s_waitcnt vmcnt(0)
	v_sub_f32_e32 v0, v3, v0
	v_add_f32_e32 v0, v165, v0
	v_cmp_gt_f32_e32 vcc, s0, v0
	s_nop 1
	v_cndmask_b32_e64 v0, 0, 1, vcc

.LBB0_413:
	s_andn2_b64 vcc, exec, s[0:1]
	s_cbranch_vccnz .LBB0_426
	s_cmp_gt_i32 s20, 0x81ff
	s_cbranch_scc1 .LBB0_426
	s_waitcnt lgkmcnt(0)
	v_lshlrev_b32_e32 v1, 3, v190
	v_and_b32_e32 v4, 64, v174
	v_and_b32_e32 v3, 8, v1
	v_xor_b32_e32 v1, 1, v174
	v_add_u32_e32 v4, 64, v4
	v_cmp_lt_i32_e32 vcc, v1, v4
	v_lshrrev_b32_e32 v0, 3, v189
	v_and_b32_e32 v2, 7, v190
	v_cndmask_b32_e32 v1, v174, v1, vcc
	s_waitcnt vmcnt(0)
	v_lshlrev_b32_e32 v81, 2, v1
	v_xor_b32_e32 v1, 2, v174
	v_cmp_lt_i32_e32 vcc, v1, v4
	v_readlane_b32 s0, v254, 54
	v_lshlrev_b32_e32 v112, 5, v2
	v_cndmask_b32_e32 v1, v174, v1, vcc
	v_lshlrev_b32_e32 v82, 2, v1
	v_xor_b32_e32 v1, 4, v174
	v_cmp_lt_i32_e32 vcc, v1, v4
	v_mul_u32_u24_e32 v4, 0x60, v0
	v_lshlrev_b32_e32 v0, 5, v190
	v_cndmask_b32_e32 v1, v174, v1, vcc
	v_lshlrev_b32_e32 v83, 2, v1
	v_and_b32_e32 v1, 2, v190
	v_cmp_eq_u32_e64 s[38:39], 0, v1
	v_readlane_b32 s1, v254, 55
	v_and_b32_e32 v0, 0x60, v0
	v_mov_b32_e32 v1, v113
	v_lshl_add_u64 v[16:17], s[0:1], 0, v[112:113]
	v_lshl_add_u64 v[18:19], s[0:1], 0, v[0:1]
	v_readlane_b32 s0, v254, 56
	v_readlane_b32 s1, v254, 57
	v_cmp_eq_u32_e32 vcc, 0, v3
	s_ashr_i32 s21, s20, 31
	v_lshl_add_u64 v[22:23], s[0:1], 0, v[0:1]
	v_mov_b32_e32 v0, 0x3f5a1371
	v_mov_b32_e32 v1, 0x3fc45f30
	v_cndmask_b32_e32 v25, v0, v1, vcc
	v_mov_b32_e32 v0, 0x305e714c
	v_mov_b32_e32 v1, 0x6dc9c883
	v_cndmask_b32_e32 v24, v0, v1, vcc
	v_mov_b32_e32 v0, 0x3f4d53c1
	v_mov_b32_e32 v1, 0x3fb6e96e
	v_cndmask_b32_e32 v27, v0, v1, vcc
	v_mov_b32_e32 v0, 0x3bd66b8
	v_mov_b32_e32 v1, 0xcaebf83f
	v_cndmask_b32_e32 v26, v0, v1, vcc
	v_mov_b32_e32 v0, 0x3f407deb
	v_mov_b32_e32 v1, 0x3fa9c4c0
	v_cndmask_b32_e32 v29, v0, v1, vcc
	v_mov_b32_e32 v0, 0x99a0e17a
	v_mov_b32_e32 v1, 0x200b604f
	v_cndmask_b32_e32 v28, v0, v1, vcc
	v_mov_b32_e32 v0, 0x3f328c52
	v_mov_b32_e32 v1, 0x3f9cfb40
	v_cndmask_b32_e32 v31, v0, v1, vcc
	v_mov_b32_e32 v0, 0xe12d9f9
	v_mov_b32_e32 v1, 0x35fd7496
	v_cndmask_b32_e32 v30, v0, v1, vcc
	v_mov_b32_e32 v0, 0x3f24dc5a
	v_mov_b32_e32 v1, 0x3f904c26
	v_cndmask_b32_e32 v33, v0, v1, vcc
	v_mov_b32_e32 v0, 0x8d185aa3
	v_mov_b32_e32 v1, 0xbe3b06cf
	v_cndmask_b32_e32 v32, v0, v1, vcc
	v_mov_b32_e32 v0, 0x3f177634
	v_mov_b32_e32 v1, 0x3f825458
	v_cndmask_b32_e32 v35, v0, v1, vcc
	v_mov_b32_e32 v0, 0x2fdebc6
	v_mov_b32_e32 v1, 0xa2566033
	v_lshl_add_u64 v[20:21], s[0:1], 0, v[112:113]
	v_cndmask_b32_e32 v34, v0, v1, vcc
	v_mov_b32_e32 v0, 0x3f0a6312
	v_mov_b32_e32 v1, 0x3f749d66
	s_lshl_b64 s[0:1], s[20:21], 9
	v_readlane_b32 s2, v251, 49
	v_cmp_gt_u32_e64 s[36:37], 4, v2
	v_cndmask_b32_e32 v37, v0, v1, vcc
	v_mov_b32_e32 v0, 0x800919d9
	v_lshlrev_b32_e32 v112, 4, v2
	v_bfe_u32 v2, v190, 3, 3
	v_readlane_b32 s3, v251, 50
	s_add_u32 s0, s2, s0
	v_cndmask_b32_e32 v36, v250, v0, vcc
	v_lshlrev_b32_e32 v0, 6, v2
	v_mov_b32_e32 v1, v113
	s_addc_u32 s1, s3, s1
	v_lshl_add_u64 v[40:41], s[0:1], 0, v[0:1]
	s_mul_i32 s0, s20, 0x1200
	v_readlane_b32 s2, v253, 19
	s_mul_hi_i32 s1, s20, 0x1200
	s_add_u32 s0, s2, s0
	v_readlane_b32 s2, v253, 20
	s_addc_u32 s1, s2, s1
	s_mul_i32 s2, s20, 0x600
	s_mul_hi_i32 s3, s20, 0x600
	s_add_u32 s2, s70, s2
	v_lshlrev_b32_e32 v0, 1, v4
	s_addc_u32 s3, s71, s3
	v_lshl_add_u64 v[42:43], s[2:3], 0, v[0:1]
	s_lshl_b64 s[2:3], s[20:21], 11
	v_readlane_b32 s4, v251, 47
	v_readlane_b32 s5, v251, 48
	s_add_u32 s2, s4, s2
	v_lshlrev_b32_e32 v0, 8, v2
	s_addc_u32 s3, s5, s3
	v_cndmask_b32_e32 v39, v182, v183, vcc
	v_cndmask_b32_e32 v38, v184, v185, vcc
	v_lshl_add_u64 v[44:45], s[2:3], 0, v[0:1]
	s_mov_b32 s4, s20
	v_readlane_b32 s5, v253, 39
	v_readlane_b32 s14, v253, 42
	global_load_dwordx4 v[192:195], v[18:19], off offset:256
	global_load_dwordx4 v[196:199], v[18:19], off offset:272
	global_load_dwordx4 v[200:203], v[16:17], off offset:16
	global_load_dwordx4 v[204:207], v[16:17], off
	global_load_dwordx4 v[208:211], v[22:23], off offset:256
	global_load_dwordx4 v[212:215], v[22:23], off offset:272
	global_load_dwordx4 v[216:219], v[20:21], off offset:16
	global_load_dwordx4 v[220:223], v[20:21], off
	s_waitcnt vmcnt(0)
	s_branch .LBB0_417

.LBB0_419:
	s_or_b64 exec, exec, s[2:3]
	v_lshl_add_u64 v[224:225], v[44:45], 0, v[112:113]
	global_load_dwordx4 v[228:231], v[224:225], off
	v_mov_b32_e32 v232, 0
	v_mov_b32_e32 v233, 0
	v_mov_b32_e32 v234, 0
	v_mov_b32_e32 v235, 0
	s_and_saveexec_b64 s[2:3], s[36:37]
	v_lshl_add_u64 v[226:227], s[0:1], 0, v[112:113]
	global_load_dwordx4 v[232:235], v[226:227], off
	s_or_b64 exec, exec, s[2:3]
	s_mov_b64 s[2:3], 0x17360000
	v_lshl_add_u64 v[64:65], v[62:63], 0, s[2:3]
	s_mul_hi_i32 s2, s4, 0x7e07e07f
	s_lshr_b32 s3, s2, 31
	s_ashr_i32 s2, s2, 12
	s_add_i32 s2, s2, s3
	s_mulk_i32 s2, 0x2080
	s_sub_i32 s2, s4, s2
	s_max_i32 s2, s2, 0x70
	s_addk_i32 s2, 0xff90
	v_cvt_f64_u32_e32 v[4:5], s2
	v_mul_f64 v[6:7], v[24:25], v[4:5]
	v_floor_f64_e32 v[6:7], v[6:7]
	v_fma_f64 v[6:7], v[24:25], v[4:5], -v[6:7]
	v_cvt_f32_f64_e32 v6, v[6:7]
	s_waitcnt vmcnt(3)
	v_cos_f32_e32 v84, v6
	v_sin_f32_e32 v85, v6
	v_mul_f64 v[6:7], v[26:27], v[4:5]
	v_floor_f64_e32 v[6:7], v[6:7]
	v_fma_f64 v[6:7], v[26:27], v[4:5], -v[6:7]
	v_cvt_f32_f64_e32 v6, v[6:7]
	v_cos_f32_e32 v46, v6
	v_sin_f32_e32 v49, v6
	v_mul_f64 v[6:7], v[28:29], v[4:5]
	v_floor_f64_e32 v[6:7], v[6:7]
	v_fma_f64 v[6:7], v[28:29], v[4:5], -v[6:7]
	v_cvt_f32_f64_e32 v6, v[6:7]
	v_cos_f32_e32 v50, v6
	v_sin_f32_e32 v52, v6
	v_mul_f64 v[6:7], v[30:31], v[4:5]
	v_floor_f64_e32 v[6:7], v[6:7]
	v_fma_f64 v[6:7], v[30:31], v[4:5], -v[6:7]
	v_cvt_f32_f64_e32 v6, v[6:7]
	v_cos_f32_e32 v51, v6
	v_sin_f32_e32 v53, v6
	v_mul_f64 v[6:7], v[32:33], v[4:5]
	v_floor_f64_e32 v[6:7], v[6:7]
	v_fma_f64 v[6:7], v[32:33], v[4:5], -v[6:7]
	v_cvt_f32_f64_e32 v6, v[6:7]
	v_cos_f32_e32 v54, v6
	v_sin_f32_e32 v56, v6
	v_mul_f64 v[6:7], v[34:35], v[4:5]
	v_floor_f64_e32 v[6:7], v[6:7]
	v_fma_f64 v[6:7], v[34:35], v[4:5], -v[6:7]
	v_cvt_f32_f64_e32 v6, v[6:7]
	v_cos_f32_e32 v55, v6
	v_sin_f32_e32 v57, v6
	v_mul_f64 v[6:7], v[36:37], v[4:5]
	v_floor_f64_e32 v[6:7], v[6:7]
	v_fma_f64 v[6:7], v[36:37], v[4:5], -v[6:7]
	v_cvt_f32_f64_e32 v6, v[6:7]
	v_cos_f32_e32 v58, v6
	v_sin_f32_e32 v60, v6
	v_mul_f64 v[6:7], v[38:39], v[4:5]
	v_floor_f64_e32 v[6:7], v[6:7]
	s_waitcnt vmcnt(0)
	v_lshlrev_b32_e32 v72, 16, v0
	v_and_b32_e32 v47, 0xffff0000, v8
	v_fma_f64 v[4:5], v[38:39], v[4:5], -v[6:7]
	v_and_b32_e32 v73, 0xffff0000, v0
	v_lshlrev_b32_e32 v70, 16, v1
	v_and_b32_e32 v71, 0xffff0000, v1
	v_lshlrev_b32_e32 v14, 16, v8
	v_mul_f32_e32 v0, v72, v72
	v_mul_f32_e32 v1, v47, v47
	v_cvt_f32_f64_e32 v4, v[4:5]
	v_fmac_f32_e32 v0, v14, v14
	v_fmac_f32_e32 v1, v73, v73
	v_cos_f32_e32 v59, v4
	v_sin_f32_e32 v61, v4
	v_lshlrev_b32_e32 v68, 16, v2
	v_and_b32_e32 v69, 0xffff0000, v2
	v_lshlrev_b32_e32 v66, 16, v3
	v_and_b32_e32 v67, 0xffff0000, v3
	v_add_f32_e32 v8, v0, v1
	v_mov_b64_e32 v[4:5], v[192:193]
	v_mov_b64_e32 v[6:7], v[194:195]
	v_mov_b64_e32 v[0:1], v[196:197]
	v_mov_b64_e32 v[2:3], v[198:199]
	v_lshlrev_b32_e32 v76, 16, v9
	v_and_b32_e32 v77, 0xffff0000, v9
	v_mul_f32_e32 v9, v76, v76
	v_fmac_f32_e32 v9, v70, v70
	v_add_f32_e32 v8, v8, v9
	v_mul_f32_e32 v9, v77, v77
	v_fmac_f32_e32 v9, v71, v71
	v_lshlrev_b32_e32 v78, 16, v10
	v_and_b32_e32 v79, 0xffff0000, v10
	v_lshlrev_b32_e32 v74, 16, v11
	v_and_b32_e32 v75, 0xffff0000, v11
	v_add_f32_e32 v11, v8, v9
	v_pk_mul_f32 v[8:9], v[78:79], v[78:79]
	v_pk_mul_f32 v[12:13], v[74:75], v[74:75]
	v_pk_fma_f32 v[8:9], v[68:69], v[68:69], v[8:9]
	v_pk_fma_f32 v[12:13], v[66:67], v[66:67], v[12:13]
	v_add_f32_e32 v8, v11, v8
	v_add_f32_e32 v8, v8, v9
	v_add_f32_e32 v8, v8, v12
	v_add_f32_e32 v8, v8, v13
	ds_bpermute_b32 v9, v81, v8
	s_mov_b32 s2, 0x3e16c740
	s_waitcnt lgkmcnt(0)
	v_add_f32_e32 v8, v8, v9
	ds_bpermute_b32 v9, v82, v8
	s_waitcnt lgkmcnt(0)
	v_add_f32_e32 v8, v8, v9
	ds_bpermute_b32 v9, v83, v8
	s_waitcnt lgkmcnt(0)
	v_add_f32_e32 v8, v8, v9
	v_fmamk_f32 v8, v8, 0x3c2aaaab, v172
	v_rsq_f32_e32 v80, v8
	s_nop 0
	v_mul_f32_e32 v8, v80, v14
	v_pk_mul_f32 v[72:73], v[80:81], v[72:73] op_sel_hi:[0,1]
	s_waitcnt vmcnt(1)
	v_mul_f32_e32 v4, v8, v4
	v_mov_b64_e32 v[8:9], v[200:201]
	v_mov_b64_e32 v[10:11], v[202:203]
	v_mov_b64_e32 v[12:13], v[204:205]
	v_mov_b64_e32 v[14:15], v[206:207]
	v_mul_f32_e32 v86, 0x3e16c740, v4
	v_mul_f32_e32 v4, v80, v47
	v_mul_f32_e32 v4, v4, v5
	v_mul_f32_e32 v48, 0x3e16c740, v4
	v_pk_mul_f32 v[4:5], v[80:81], v[70:71] op_sel_hi:[0,1]
	ds_bpermute_b32 v47, v82, v48
	s_waitcnt vmcnt(0)
	v_pk_mul_f32 v[4:5], v[4:5], v[14:15]
	s_nop 0
	v_pk_mul_f32 v[14:15], v[4:5], s[2:3] op_sel_hi:[1,0]
	v_pk_mul_f32 v[4:5], v[80:81], v[76:77] op_sel_hi:[0,1]
	v_pk_mul_f32 v[4:5], v[4:5], v[6:7]
	v_pk_mul_f32 v[6:7], v[80:81], v[68:69] op_sel_hi:[0,1]
	v_pk_mul_f32 v[6:7], v[6:7], v[8:9]
	v_pk_mul_f32 v[12:13], v[72:73], v[12:13]
	v_pk_mul_f32 v[68:69], v[6:7], s[2:3] op_sel_hi:[1,0]
	v_pk_mul_f32 v[6:7], v[80:81], v[78:79] op_sel_hi:[0,1]
	v_pk_mul_f32 v[0:1], v[6:7], v[0:1]
	v_pk_mul_f32 v[6:7], v[80:81], v[66:67] op_sel_hi:[0,1]
	v_pk_mul_f32 v[6:7], v[6:7], v[10:11]
	v_pk_mul_f32 v[4:5], v[4:5], s[2:3] op_sel_hi:[1,0]
	v_pk_mul_f32 v[70:71], v[6:7], s[2:3] op_sel_hi:[1,0]
	v_pk_mul_f32 v[6:7], v[80:81], v[74:75] op_sel_hi:[0,1]
	v_pk_mul_f32 v[2:3], v[6:7], v[2:3]
	v_pk_mul_f32 v[0:1], v[0:1], s[2:3] op_sel_hi:[1,0]
	v_pk_mul_f32 v[8:9], v[2:3], s[2:3] op_sel_hi:[1,0]
	v_pk_mul_f32 v[72:73], v[12:13], s[2:3] op_sel_hi:[1,0]
	ds_bpermute_b32 v12, v82, v86
	ds_bpermute_b32 v2, v82, v4
	ds_bpermute_b32 v3, v82, v5
	ds_bpermute_b32 v6, v82, v0
	ds_bpermute_b32 v7, v82, v1
	ds_bpermute_b32 v10, v82, v8
	ds_bpermute_b32 v11, v82, v9
	v_cvt_pk_bf16_f32 v66, v72, v73
	v_cvt_pk_bf16_f32 v67, v14, v15
	v_cvt_pk_bf16_f32 v68, v68, v69
	v_cvt_pk_bf16_f32 v69, v70, v71
	global_store_dwordx4 v[64:65], v[66:69], off
	s_and_saveexec_b64 s[2:3], s[36:37]
	s_cbranch_execz .LBB0_421
	s_waitcnt lgkmcnt(0)
	v_pk_mul_f32 v[10:11], v[60:61], v[10:11]
	v_pk_mul_f32 v[6:7], v[56:57], v[6:7]
	v_pk_fma_f32 v[14:15], v[8:9], v[58:59], v[10:11] neg_lo:[0,0,1] neg_hi:[0,0,1]
	v_pk_fma_f32 v[8:9], v[8:9], v[58:59], v[10:11]
	s_nop 0
	v_cndmask_b32_e64 v10, v9, v15, s[38:39]
	v_cndmask_b32_e64 v11, v8, v14, s[38:39]
	v_pk_fma_f32 v[8:9], v[0:1], v[54:55], v[6:7] neg_lo:[0,0,1] neg_hi:[0,0,1]
	v_pk_fma_f32 v[0:1], v[0:1], v[54:55], v[6:7]
	s_nop 0
	v_cndmask_b32_e64 v6, v1, v9, s[38:39]
	v_cndmask_b32_e64 v7, v0, v8, s[38:39]
	v_pk_mul_f32 v[0:1], v[52:53], v[2:3]
	s_nop 0
	v_pk_fma_f32 v[2:3], v[4:5], v[50:51], v[0:1] neg_lo:[0,0,1] neg_hi:[0,0,1]
	v_pk_fma_f32 v[0:1], v[4:5], v[50:51], v[0:1]
	s_nop 0
	v_cndmask_b32_e64 v2, v0, v2, s[38:39]
	v_mul_f32_e32 v0, v85, v12
	v_cndmask_b32_e64 v3, v1, v3, s[38:39]
	v_cndmask_b32_e64 v4, v0, -v0, s[38:39]
	v_pk_mul_f32 v[0:1], v[48:49], v[46:47]
	v_fmac_f32_e32 v4, v86, v84
	v_sub_f32_e32 v5, v0, v1
	v_add_f32_e32 v0, v0, v1
	v_cndmask_b32_e64 v0, v0, v5, s[38:39]
	v_cvt_pk_bf16_f32 v0, v4, v0
	v_add_co_u32_e32 v4, vcc, 0x17360000, v62
	v_cvt_pk_bf16_f32 v1, v2, v3
	v_cvt_pk_bf16_f32 v2, v7, v6
	v_cvt_pk_bf16_f32 v3, v11, v10
	v_addc_co_u32_e32 v5, vcc, 0, v63, vcc
	global_store_dwordx4 v[4:5], v[0:3], off offset:128
.LBB0_421:
	s_or_b64 exec, exec, s[2:3]
	s_waitcnt lgkmcnt(6)
	v_lshl_add_u64 v[12:13], v[44:45], 0, v[112:113]
	s_waitcnt lgkmcnt(4)
	v_mov_b64_e32 v[0:1], v[228:229]
	v_mov_b64_e32 v[2:3], v[230:231]
	v_mov_b32_e32 v8, 0
	v_mov_b32_e32 v9, 0
	s_waitcnt lgkmcnt(1)
	v_mov_b32_e32 v10, 0
	s_waitcnt lgkmcnt(0)
	v_mov_b32_e32 v11, 0
	s_and_saveexec_b64 s[2:3], s[36:37]
	s_cbranch_execz .LBB0_423
	v_lshl_add_u64 v[4:5], s[0:1], 0, v[112:113]
	v_mov_b64_e32 v[8:9], v[232:233]
	v_mov_b64_e32 v[10:11], v[234:235]
.LBB0_423:
	s_or_b64 exec, exec, s[2:3]
	v_lshlrev_b32_e32 v66, 16, v0
	v_and_b32_e32 v48, 0xffff0000, v8
	v_and_b32_e32 v67, 0xffff0000, v0
	v_lshlrev_b32_e32 v64, 16, v1
	v_and_b32_e32 v65, 0xffff0000, v1
	v_lshlrev_b32_e32 v47, 16, v8
	v_mul_f32_e32 v0, v66, v66
	v_mul_f32_e32 v1, v48, v48
	v_fmac_f32_e32 v0, v47, v47
	v_fmac_f32_e32 v1, v67, v67
	v_lshlrev_b32_e32 v62, 16, v2
	v_and_b32_e32 v63, 0xffff0000, v2
	v_lshlrev_b32_e32 v14, 16, v3
	v_and_b32_e32 v15, 0xffff0000, v3
	v_add_f32_e32 v8, v0, v1
	v_mov_b64_e32 v[4:5], v[208:209]
	v_mov_b64_e32 v[6:7], v[210:211]
	v_mov_b64_e32 v[0:1], v[212:213]
	v_mov_b64_e32 v[2:3], v[214:215]
	v_lshlrev_b32_e32 v74, 16, v9
	v_and_b32_e32 v75, 0xffff0000, v9
	v_mul_f32_e32 v9, v74, v74
	v_lshlrev_b32_e32 v68, 16, v11
	v_and_b32_e32 v69, 0xffff0000, v11
	v_fmac_f32_e32 v9, v64, v64
	v_pk_mul_f32 v[70:71], v[68:69], v[68:69]
	v_add_f32_e32 v8, v8, v9
	v_mul_f32_e32 v9, v75, v75
	v_pk_fma_f32 v[72:73], v[14:15], v[14:15], v[70:71]
	v_fmac_f32_e32 v9, v65, v65
	v_lshlrev_b32_e32 v70, 16, v10
	v_and_b32_e32 v71, 0xffff0000, v10
	v_add_f32_e32 v11, v8, v9
	v_pk_mul_f32 v[8:9], v[70:71], v[70:71]
	s_nop 0
	v_pk_fma_f32 v[8:9], v[62:63], v[62:63], v[8:9]
	s_nop 0
	v_add_f32_e32 v8, v11, v8
	v_add_f32_e32 v8, v8, v9
	v_add_f32_e32 v8, v8, v72
	v_add_f32_e32 v8, v8, v73
	ds_bpermute_b32 v9, v81, v8
	s_waitcnt lgkmcnt(0)
	v_add_f32_e32 v8, v8, v9
	ds_bpermute_b32 v9, v82, v8
	s_waitcnt lgkmcnt(0)
	v_add_f32_e32 v8, v8, v9
	ds_bpermute_b32 v9, v83, v8
	s_waitcnt lgkmcnt(0)
	v_add_f32_e32 v8, v8, v9
	v_fmamk_f32 v8, v8, 0x3c2aaaab, v172
	v_rsq_f32_e32 v72, v8
	s_nop 0
	v_mul_f32_e32 v8, v72, v47
	v_mul_f32_e32 v73, v8, v4
	v_mov_b64_e32 v[8:9], v[216:217]
	v_mov_b64_e32 v[10:11], v[218:219]
	v_mov_b64_e32 v[76:77], v[220:221]
	v_mov_b64_e32 v[78:79], v[222:223]
	v_mul_f32_e32 v4, v72, v48
	v_mul_f32_e32 v48, v4, v5
	v_pk_mul_f32 v[4:5], v[72:73], v[64:65] op_sel_hi:[0,1]
	ds_bpermute_b32 v47, v82, v48
	v_pk_mul_f32 v[66:67], v[72:73], v[66:67] op_sel_hi:[0,1]
	v_pk_mul_f32 v[64:65], v[4:5], v[78:79]
	v_pk_mul_f32 v[4:5], v[72:73], v[74:75] op_sel_hi:[0,1]
	v_pk_mul_f32 v[4:5], v[4:5], v[6:7]
	v_pk_mul_f32 v[6:7], v[72:73], v[62:63] op_sel_hi:[0,1]
	v_pk_mul_f32 v[74:75], v[6:7], v[8:9]
	v_pk_mul_f32 v[6:7], v[72:73], v[70:71] op_sel_hi:[0,1]
	v_pk_mul_f32 v[0:1], v[6:7], v[0:1]
	v_pk_mul_f32 v[6:7], v[72:73], v[14:15] op_sel_hi:[0,1]
	v_pk_mul_f32 v[70:71], v[6:7], v[10:11]
	v_pk_mul_f32 v[6:7], v[72:73], v[68:69] op_sel_hi:[0,1]
	v_pk_mul_f32 v[8:9], v[6:7], v[2:3]
	ds_bpermute_b32 v14, v82, v73
	ds_bpermute_b32 v2, v82, v4
	ds_bpermute_b32 v3, v82, v5
	ds_bpermute_b32 v6, v82, v0
	ds_bpermute_b32 v7, v82, v1
	ds_bpermute_b32 v10, v82, v8
	ds_bpermute_b32 v11, v82, v9
	v_pk_mul_f32 v[66:67], v[66:67], v[76:77]
	v_cvt_pk_bf16_f32 v63, v64, v65
	v_cvt_pk_bf16_f32 v62, v66, v67
	v_cvt_pk_bf16_f32 v64, v74, v75
	v_cvt_pk_bf16_f32 v65, v70, v71
	global_store_dwordx4 v[12:13], v[62:65], off
	s_and_saveexec_b64 s[2:3], s[36:37]
	s_cbranch_execz .LBB0_416
	s_waitcnt lgkmcnt(0)
	v_pk_mul_f32 v[10:11], v[60:61], v[10:11]
	v_pk_mul_f32 v[6:7], v[56:57], v[6:7]
	v_pk_fma_f32 v[12:13], v[8:9], v[58:59], v[10:11] neg_lo:[0,0,1] neg_hi:[0,0,1]
	v_pk_fma_f32 v[8:9], v[8:9], v[58:59], v[10:11]
	s_nop 0
	v_cndmask_b32_e64 v10, v9, v13, s[38:39]
	v_cndmask_b32_e64 v11, v8, v12, s[38:39]
	v_pk_fma_f32 v[8:9], v[0:1], v[54:55], v[6:7] neg_lo:[0,0,1] neg_hi:[0,0,1]
	v_pk_fma_f32 v[0:1], v[0:1], v[54:55], v[6:7]
	s_nop 0
	v_cndmask_b32_e64 v6, v1, v9, s[38:39]
	v_cndmask_b32_e64 v7, v0, v8, s[38:39]
	v_pk_mul_f32 v[0:1], v[52:53], v[2:3]
	s_nop 0
	v_pk_fma_f32 v[2:3], v[4:5], v[50:51], v[0:1] neg_lo:[0,0,1] neg_hi:[0,0,1]
	v_pk_fma_f32 v[0:1], v[4:5], v[50:51], v[0:1]
	s_nop 0
	v_cndmask_b32_e64 v2, v0, v2, s[38:39]
	v_mul_f32_e32 v0, v85, v14
	v_cndmask_b32_e64 v3, v1, v3, s[38:39]
	v_cndmask_b32_e64 v8, v0, -v0, s[38:39]
	v_pk_mul_f32 v[0:1], v[48:49], v[46:47]
	v_fmac_f32_e32 v8, v73, v84
	v_sub_f32_e32 v4, v0, v1
	v_add_f32_e32 v0, v0, v1
	v_cndmask_b32_e64 v0, v0, v4, s[38:39]
	v_lshl_add_u64 v[4:5], v[40:41], 0, v[112:113]
	v_cvt_pk_bf16_f32 v0, v8, v0
	v_cvt_pk_bf16_f32 v1, v2, v3
	v_cvt_pk_bf16_f32 v2, v7, v6
	v_cvt_pk_bf16_f32 v3, v11, v10
	global_store_dwordx4 v[4:5], v[0:3], off
	s_branch .LBB0_416
